# in-proj epilogue: bf16 output tile transposed through LDS so stores are full 128-byte rows (dwordx4) instead of scattered 8-byte pieces; in-proj prologue loads issued before the tile-top barrier
# speedup vs baseline: 1.0637x; 1.0269x over previous
.LBB0_190:
	s_ashr_i32 s12, s33, 3
	s_mul_hi_i32 s13, s12, 0x38e38e39
	s_lshr_b32 s23, s13, 31
	s_ashr_i32 s13, s13, 1
	s_add_i32 s13, s13, s23
	s_mul_i32 s23, s13, 9
	s_sub_i32 s23, s12, s23
	s_lshl_b32 s12, s33, 8
	v_mbcnt_lo_u32_b32 v0, -1, 0
	v_mbcnt_hi_u32_b32 v0, -1, v0
	s_lshl_b32 s63, s13, 11
	s_and_b32 s12, s12, 0x700
	v_add_u32_e32 v0, s3, v0
	s_or_b32 s12, s63, s12
	s_lshl_b32 s88, s23, 8
	s_ashr_i32 s89, s88, 31
	s_cmpk_lt_u32 s3, 0x100
	s_cbranch_scc1 .Lip_sw_issue
	v_add_u32_e32 v42, 0xffffff00, v0
	v_add_u32_e32 v32, s12, v42
	v_ashrrev_i32_e32 v33, 31, v32
	v_lshlrev_b64 v[32:33], 5, v[32:33]
	v_lshl_add_u64 v[36:37], s[8:9], 0, v[32:33]
	global_load_dwordx4 v[32:35], v[36:37], off
	s_nop 0
	global_load_dwordx4 v[36:39], v[36:37], off offset:16
	s_branch .Lip_issue_done
.Lip_sw_issue:
	s_add_i32 s13, s63, 0xfffff000
	s_lshr_b32 s13, s13, 11
	s_add_i32 s13, s13, 1
	s_cmpk_gt_i32 s12, 0xfff
	s_cselect_b32 s13, s13, 0
	s_mul_i32 s23, s86, 5
	s_add_i32 s13, s13, s23
	s_mul_hi_u32 s23, s13, 0x2400
	s_mulk_i32 s13, 0x2400
	s_add_u32 s13, s21, s13
	s_addc_u32 s23, s24, s23
	s_lshl_b64 s[54:55], s[88:89], 2
	s_add_u32 s54, s13, s54
	s_addc_u32 s55, s23, s55
	v_mov_b32_e32 v44, v0
	v_ashrrev_i32_e32 v45, 31, v0
	v_lshl_add_u64 v[32:33], v[44:45], 2, s[54:55]
	s_mov_b64 s[54:55], 0x2d000
	global_load_dword v48, v[32:33], off
	v_lshl_add_u64 v[34:35], v[32:33], 0, s[54:55]
	global_load_dword v49, v[34:35], off
	v_lshl_add_u64 v[34:35], v[34:35], 0, s[54:55]
	global_load_dword v50, v[34:35], off
	v_lshl_add_u64 v[34:35], v[34:35], 0, s[54:55]
	global_load_dword v51, v[34:35], off
	v_lshl_add_u64 v[34:35], v[34:35], 0, s[54:55]
	global_load_dword v52, v[34:35], off
	v_lshl_add_u64 v[34:35], v[34:35], 0, s[54:55]
	global_load_dword v53, v[34:35], off
	v_lshl_add_u64 v[34:35], v[34:35], 0, s[54:55]
	global_load_dword v54, v[34:35], off
	v_lshl_add_u64 v[34:35], v[34:35], 0, s[54:55]
	global_load_dword v55, v[34:35], off
	v_lshl_add_u64 v[34:35], v[34:35], 0, s[54:55]
	global_load_dword v56, v[34:35], off
	v_lshl_add_u64 v[34:35], v[34:35], 0, s[54:55]
	global_load_dword v57, v[34:35], off
	v_lshl_add_u64 v[34:35], v[34:35], 0, s[54:55]
	global_load_dword v58, v[34:35], off
	v_lshl_add_u64 v[34:35], v[34:35], 0, s[54:55]
	global_load_dword v59, v[34:35], off
	v_lshl_add_u64 v[34:35], v[34:35], 0, s[54:55]
	global_load_dword v60, v[34:35], off
	v_lshl_add_u64 v[34:35], v[34:35], 0, s[54:55]
	global_load_dword v61, v[34:35], off
	v_lshl_add_u64 v[34:35], v[34:35], 0, s[54:55]
	global_load_dword v62, v[34:35], off
	v_lshl_add_u64 v[34:35], v[34:35], 0, s[54:55]
	global_load_dword v63, v[34:35], off
.Lip_issue_done:
	v_mov_b64_e32 v[2:3], s[88:89]
	v_mbcnt_lo_u32_b32 v7, -1, 0
	v_mbcnt_hi_u32_b32 v7, -1, v7
	v_lshlrev_b64 v[0:1], 11, v[2:3]
	v_add_u32_e32 v148, s3, v7
	v_ashrrev_i32_e32 v3, 31, v148
	v_lshrrev_b32_e32 v3, 26, v3
	v_add_u32_e32 v3, v148, v3
	v_ashrrev_i32_e32 v6, 6, v3
	v_bfe_i32 v3, v148, 27, 1
	v_lshlrev_b32_e32 v2, 4, v148
	v_lshrrev_b32_e32 v3, 22, v3
	v_add_u32_e32 v3, v2, v3
	v_and_b32_e32 v3, 0xfffffc00, v3
	v_sub_u32_e32 v3, v2, v3
	v_lshrrev_b32_e32 v4, 4, v3
	v_bitop3_b32 v3, v4, v3, 32 bitop3:0x6c
	v_ashrrev_i32_e32 v5, 31, v3
	v_lshrrev_b32_e32 v5, 26, v5
	v_add_u32_e32 v5, v3, v5
	v_ashrrev_i32_e32 v9, 6, v5
	v_and_b32_e32 v5, 0xc0, v5
	v_sub_u32_e32 v3, v3, v5
	v_lshlrev_b32_e32 v4, 3, v6
	v_lshlrev_b32_e32 v10, 5, v6
	v_ashrrev_i16_sdwa v3, v247, sext(v3) dst_sel:DWORD dst_unused:UNUSED_PAD src0_sel:DWORD src1_sel:BYTE_0
	v_and_b32_e32 v4, 0x1ffff0, v4
	v_and_b32_e32 v11, 32, v10
	v_bfe_i32 v10, v3, 0, 16
	v_add_u32_e32 v3, v11, v10
	v_add_lshl_u32 v4, v9, v4, 11
	v_add_u32_e32 v2, 0x2000, v2
	v_lshl_add_u32 v198, v3, 1, v4
	v_ashrrev_i32_e32 v3, 31, v2
	v_lshrrev_b32_e32 v3, 22, v3
	v_add_u32_e32 v3, v2, v3
	v_ashrrev_i32_e32 v11, 10, v3
	v_mul_i32_i24_e32 v3, 0x400, v11
	v_sub_u32_e32 v2, v2, v3
	v_lshrrev_b32_e32 v3, 4, v2
	v_bitop3_b32 v2, v3, v2, 32 bitop3:0x6c
	v_ashrrev_i32_e32 v4, 31, v2
	v_lshrrev_b32_e32 v4, 26, v4
	v_add_u32_e32 v4, v2, v4
	v_ashrrev_i32_e32 v12, 6, v4
	v_and_b32_e32 v4, 0xc0, v4
	s_ashr_i32 s13, s12, 31
	v_sub_u32_e32 v2, v2, v4
	s_lshl_b64 s[52:53], s[12:13], 11
	v_lshlrev_b32_e32 v3, 3, v11
	v_lshlrev_b32_e32 v5, 5, v11
	v_ashrrev_i16_sdwa v2, v247, sext(v2) dst_sel:DWORD dst_unused:UNUSED_PAD src0_sel:DWORD src1_sel:BYTE_0
	s_add_u32 s52, s19, s52
	v_and_b32_e32 v3, 0x1ffff0, v3
	v_and_b32_e32 v5, 32, v5
	v_bfe_i32 v13, v2, 0, 16
	s_addc_u32 s53, s20, s53
	v_add_u32_e32 v2, v5, v13
	v_add_lshl_u32 v3, v12, v3, 11
	s_mov_b32 m0, s14
	v_lshl_add_u64 v[128:129], s[4:5], 0, v[0:1]
	v_lshl_add_u32 v130, v2, 1, v3
	global_load_lds_dwordx4 v198, s[52:53]
	s_mov_b32 m0, s60
	v_mov_b32_e32 v131, v199
	global_load_lds_dwordx4 v130, s[52:53]
	v_lshl_add_u64 v[2:3], v[128:129], 0, v[198:199]
	s_mov_b32 m0, s27
	s_add_i32 s13, s27, 0x2000
	global_load_lds_dwordx4 v[2:3], off
	v_lshl_add_u64 v[4:5], v[128:129], 0, v[130:131]
	s_mov_b32 m0, s13
	s_add_u32 s54, s52, 0x40000
	global_load_lds_dwordx4 v[4:5], off
	s_addc_u32 s55, s53, 0
	s_mov_b32 m0, s26
	v_ashrrev_i32_e32 v8, 8, v148
	global_load_lds_dwordx4 v198, s[54:55]
	s_mov_b32 m0, s67
	global_load_lds_dwordx4 v130, s[54:55]
	s_mov_b64 s[54:55], 0x40000
	v_lshl_add_u64 v[14:15], v[128:129], 0, s[54:55]
	v_lshl_add_u64 v[16:17], v[14:15], 0, v[198:199]
	s_mov_b32 m0, s56
	v_lshl_add_u64 v[14:15], v[14:15], 0, v[130:131]
	global_load_lds_dwordx4 v[16:17], off
	s_mov_b32 m0, s57
	s_nop 0
	global_load_lds_dwordx4 v[14:15], off
	s_waitcnt vmcnt(8)
	s_cmpk_lt_u32 s3, 0x100
	s_cbranch_scc1 .Lip_sw_sum
	s_mov_b32 s90, 0x800000
	v_mov_b32_e32 v40, v32
	v_mov_b32_e32 v41, v36
	v_mov_b32_e32 v36, v33
	v_mov_b32_e32 v32, v34
	v_mov_b32_e32 v33, v38
	v_mov_b32_e32 v38, v35
	v_pk_add_f32 v[34:35], v[40:41], v[36:37]
	v_pk_add_f32 v[32:33], v[32:33], v[38:39]
	s_nop 0
	v_pk_add_f32 v[32:33], v[34:35], v[32:33]
	s_nop 0
	v_add_f32_e32 v32, v32, v33
	v_fmamk_f32 v32, v32, 0x3a800000, v196
	v_mul_f32_e32 v33, 0x4b800000, v32
	v_cmp_gt_f32_e32 vcc, s90, v32
	s_nop 1
	v_cndmask_b32_e32 v32, v32, v33, vcc
	v_rsq_f32_e32 v32, v32
	v_lshl_add_u32 v41, v42, 2, v248
	v_mul_f32_e32 v34, 0x45800000, v32
	v_cndmask_b32_e32 v33, v32, v34, vcc
	s_branch .Lip_sum_done
.Lip_sw_sum:
	v_add_f32_e32 v33, 0, v48
	v_add_f32_e32 v33, v33, v49
	v_add_f32_e32 v33, v33, v50
	v_add_f32_e32 v33, v33, v51
	v_add_f32_e32 v33, v33, v52
	v_add_f32_e32 v33, v33, v53
	v_add_f32_e32 v33, v33, v54
	v_add_f32_e32 v33, v33, v55
	v_add_f32_e32 v33, v33, v56
	v_add_f32_e32 v33, v33, v57
	v_add_f32_e32 v33, v33, v58
	v_add_f32_e32 v33, v33, v59
	v_add_f32_e32 v33, v33, v60
	v_add_f32_e32 v33, v33, v61
	v_add_f32_e32 v33, v33, v62
	v_add_f32_e32 v33, v33, v63
	v_mov_b32_e32 v34, 0x21000
	v_lshl_add_u32 v41, v44, 2, v34
.Lip_sum_done:
	s_waitcnt lgkmcnt(0)
	s_barrier
	s_cmpk_lt_i32 s33, 0x100
	s_cbranch_scc1 .Lsig_skip
	s_cmpk_ge_i32 s33, 0x190
	s_cbranch_scc1 .Lsig_skip
	s_cmp_lg_u32 s3, 0
	s_cbranch_scc1 .Lsig_skip
	s_mov_b64 s[92:93], exec
	s_mov_b64 exec, 1
	s_and_b32 s90, s85, 7
	s_lshl_b32 s90, s90, 8
	s_add_i32 s90, s90, 0xb8fc480
	v_mov_b32_e32 v50, s90
	v_mov_b32_e32 v51, 1
	global_atomic_add v50, v51, s[28:29]
	s_mov_b64 exec, s[92:93]
.Lsig_skip:
	ds_write_b32 v41, v33
	v_cmp_eq_u32_e32 vcc, 1, v8
	s_and_saveexec_b64 s[54:55], vcc
	s_cbranch_execz .LBB0_196
	s_barrier

.LBB0_200:
	s_or_b64 exec, exec, s[52:53]
	v_mbcnt_lo_u32_b32 v204, -1, 0
	v_mbcnt_hi_u32_b32 v204, -1, v204
	s_lshr_b32 s101, s3, 6
	s_mulk_i32 s101, 0xa00
	s_add_i32 s101, s101, 0x8000
	v_and_b32_e32 v205, 15, v204
	v_lshrrev_b32_e32 v206, 4, v204
	v_lshrrev_b32_e32 v207, 3, v204
	v_and_b32_e32 v208, 7, v204
	v_mul_u32_u24_e32 v200, 0x90, v205
	v_lshl_add_u32 v200, v206, 3, v200
	v_add_u32_e32 v200, s101, v200
	v_mul_u32_u24_e32 v201, 0x90, v207
	v_lshl_add_u32 v201, v208, 4, v201
	v_add_u32_e32 v201, s101, v201
	v_sub_u32_e32 v202, v207, v205
	v_mul_i32_i24_e32 v202, 0x1200, v202
	v_lshl_add_u32 v202, v208, 4, v202
	v_lshlrev_b32_e32 v206, 3, v206
	v_sub_u32_e32 v202, v202, v206
	v_ashrrev_i32_e32 v203, 31, v202
	s_mov_b64 s[100:101], 0x9000
	v_mbcnt_lo_u32_b32 v32, -1, 0
	v_mbcnt_hi_u32_b32 v32, -1, v32
	s_cmpk_gt_i32 s12, 0xfff
	v_add_u32_e32 v33, s3, v32
	v_and_b32_e32 v40, 15, v32
	v_bfe_u32 v148, v32, 4, 2
	v_lshrrev_b32_e32 v32, 1, v33
	v_and_b32_e32 v41, 0x60, v32
	v_ashrrev_i32_e32 v149, 2, v33
	v_or_b32_e32 v167, v41, v40
	v_and_b32_e32 v158, 0xffffffc0, v149
	v_lshlrev_b32_e32 v32, 4, v148
	v_or_b32_e32 v150, s12, v167
	v_lshl_or_b32 v32, v158, 2, v32
	v_lshl_or_b32 v33, v167, 2, v248
	v_add_u32_e32 v155, 0x21000, v32
	v_lshrrev_b32_e32 v36, 6, v150
	ds_read_b32 v160, v33
	v_and_b32_e32 v151, 29, v36
	s_waitcnt vmcnt(0)
	ds_read_b128 v[36:39], v155 offset:64
	ds_read_b128 v[32:35], v155
	v_bitop3_b32 v153, v41, 47, v40 bitop3:0xc8
	v_add_u32_e32 v152, s88, v158
	s_cselect_b64 s[52:53], -1, 0
	v_lshl_or_b32 v166, v148, 5, v241
	s_waitcnt lgkmcnt(0)
	v_pk_fma_f32 v[60:61], v[46:47], v[160:161], v[32:33] op_sel_hi:[1,0,1]
	ds_read_b128 v[40:43], v155 offset:128
	ds_read_b128 v[44:47], v155 offset:192
	v_cmp_gt_i32_e32 vcc, s18, v152
	v_pk_fma_f32 v[52:53], v[52:53], v[160:161], v[36:37] op_sel_hi:[1,0,1]
	v_pk_fma_f32 v[62:63], v[48:49], v[160:161], v[34:35] op_sel_hi:[1,0,1]
	v_pk_fma_f32 v[54:55], v[54:55], v[160:161], v[38:39] op_sel_hi:[1,0,1]
	s_waitcnt lgkmcnt(1)
	v_pk_fma_f32 v[56:57], v[56:57], v[160:161], v[40:41] op_sel_hi:[1,0,1]
	s_waitcnt lgkmcnt(0)
	v_pk_fma_f32 v[48:49], v[144:145], v[160:161], v[44:45] op_sel_hi:[1,0,1]
	v_pk_fma_f32 v[58:59], v[58:59], v[160:161], v[42:43] op_sel_hi:[1,0,1]
	v_pk_fma_f32 v[50:51], v[146:147], v[160:161], v[46:47] op_sel_hi:[1,0,1]
	s_and_b64 s[90:91], s[52:53], vcc
	v_lshl_add_u32 v159, v151, 7, v166
	v_lshl_add_u32 v169, v153, 7, v166
	s_and_saveexec_b64 s[54:55], s[90:91]
	s_cbranch_execz .LBB0_202
	ds_read_b128 v[144:147], v159
	ds_read_b128 v[162:165], v159 offset:16
	s_waitcnt lgkmcnt(1)
	v_mov_b32_e32 v157, v146
	v_mov_b32_e32 v146, v145
	v_mov_b32_e32 v156, v144
	v_pk_mul_f32 v[144:145], v[52:53], v[146:147]
	s_nop 0
	v_pk_fma_f32 v[170:171], v[60:61], v[156:157], v[144:145] neg_lo:[0,0,1] neg_hi:[0,0,1]
	v_pk_mul_f32 v[60:61], v[60:61], v[146:147]
	s_nop 0
	v_pk_fma_f32 v[52:53], v[52:53], v[156:157], v[60:61]
	s_waitcnt lgkmcnt(0)
	v_mov_b32_e32 v61, v164
	v_mov_b32_e32 v164, v163
	v_mov_b32_e32 v60, v162
	v_pk_mul_f32 v[144:145], v[54:55], v[164:165]
	s_nop 0
	v_pk_fma_f32 v[156:157], v[62:63], v[60:61], v[144:145] neg_lo:[0,0,1] neg_hi:[0,0,1]
	v_pk_mul_f32 v[62:63], v[62:63], v[164:165]
	s_nop 0
	v_pk_fma_f32 v[54:55], v[54:55], v[60:61], v[62:63]
	ds_read_b128 v[60:63], v169
	ds_read_b128 v[144:147], v169 offset:16
	s_waitcnt lgkmcnt(1)
	v_mov_b32_e32 v163, v62
	v_mov_b32_e32 v62, v61
	v_mov_b32_e32 v162, v60
	v_pk_mul_f32 v[60:61], v[48:49], v[62:63]
	s_nop 0
	v_pk_fma_f32 v[164:165], v[56:57], v[162:163], v[60:61] neg_lo:[0,0,1] neg_hi:[0,0,1]
	v_pk_mul_f32 v[56:57], v[56:57], v[62:63]
	v_mov_b64_e32 v[62:63], v[156:157]
	v_pk_fma_f32 v[48:49], v[48:49], v[162:163], v[56:57]
	s_waitcnt lgkmcnt(0)
	v_mov_b32_e32 v57, v146
	v_mov_b32_e32 v146, v145
	v_mov_b32_e32 v56, v144
	v_pk_mul_f32 v[60:61], v[50:51], v[146:147]
	s_nop 0
	v_pk_fma_f32 v[144:145], v[58:59], v[56:57], v[60:61] neg_lo:[0,0,1] neg_hi:[0,0,1]
	v_pk_mul_f32 v[58:59], v[58:59], v[146:147]
	v_mov_b64_e32 v[60:61], v[170:171]
	v_pk_fma_f32 v[50:51], v[50:51], v[56:57], v[58:59]
	v_mov_b64_e32 v[56:57], v[164:165]
	v_mov_b64_e32 v[58:59], v[144:145]
.LBB0_202:
	s_or_b64 exec, exec, s[54:55]
	s_lshr_b32 s13, s12, 6
	s_or_b32 s13, s13, s86
	v_lshlrev_b32_e32 v198, 3, v148
	s_lshl_b32 s23, s13, 8
	v_cmp_gt_i32_e32 vcc, s22, v152
	v_lshl_add_u64 v[156:157], s[6:7], 0, v[198:199]
	v_or_b32_e32 v144, s23, v167
	v_cndmask_b32_e32 v154, 1.0, v249, vcc
	v_lshlrev_b32_e32 v151, 2, v148
	v_and_b32_e32 v161, 64, v149
	v_mad_i64_i32 v[164:165], s[54:55], v150, s62, v[156:157]
	v_ashrrev_i32_e32 v145, 31, v144
	v_ashrrev_i32_e32 v153, 31, v152
	v_pk_mul_f32 v[146:147], v[154:155], v[60:61] op_sel_hi:[0,1]
	v_pk_mul_f32 v[148:149], v[154:155], v[62:63] op_sel_hi:[0,1]
	v_lshlrev_b64 v[162:163], 9, v[144:145]
	v_lshl_add_u64 v[144:145], v[152:153], 1, v[164:165]
	v_cvt_pk_bf16_f32 v146, v146, v147
	v_cvt_pk_bf16_f32 v147, v148, v149
	ds_write_b64 v200, v[146:147]
	v_pk_mul_f32 v[146:147], v[154:155], v[52:53] op_sel_hi:[0,1]
	v_pk_mul_f32 v[148:149], v[154:155], v[54:55] op_sel_hi:[0,1]
	v_cvt_pk_bf16_f32 v146, v146, v147
	v_cvt_pk_bf16_f32 v147, v148, v149
	ds_write_b64 v200, v[146:147] offset:32
	v_pk_mul_f32 v[146:147], v[154:155], v[56:57] op_sel_hi:[0,1]
	v_pk_mul_f32 v[148:149], v[154:155], v[58:59] op_sel_hi:[0,1]
	v_cvt_pk_bf16_f32 v146, v146, v147
	v_cvt_pk_bf16_f32 v147, v148, v149
	ds_write_b64 v200, v[146:147] offset:64
	v_pk_mul_f32 v[146:147], v[154:155], v[48:49] op_sel_hi:[0,1]
	v_pk_mul_f32 v[148:149], v[154:155], v[50:51] op_sel_hi:[0,1]
	v_cvt_pk_bf16_f32 v146, v146, v147
	v_cvt_pk_bf16_f32 v147, v148, v149
	ds_write_b64 v200, v[146:147] offset:96
	s_waitcnt lgkmcnt(0)
	ds_read_b128 v[204:207], v201
	ds_read_b128 v[208:211], v201 offset:1152
	v_lshl_add_u64 v[212:213], v[144:145], 0, v[202:203]
	v_lshl_add_u64 v[214:215], v[212:213], 0, s[100:101]
	s_waitcnt lgkmcnt(0)
	global_store_dwordx4 v[212:213], v[204:207], off
	global_store_dwordx4 v[214:215], v[208:211], off
	v_and_b32_e32 v144, 0xffffff00, v152
	v_cmp_eq_u32_e32 vcc, s22, v144
	s_xor_b64 s[54:55], s[52:53], -1
	s_and_b64 s[92:93], s[54:55], vcc
	v_and_b32_e32 v168, 0x280, v152
	v_lshlrev_b32_e32 v150, 2, v161
	v_lshlrev_b32_e32 v148, 2, v151
	s_and_saveexec_b64 s[94:95], s[92:93]
	s_cbranch_execz .LBB0_204
	v_cmp_eq_u32_e32 vcc, s18, v168
	v_mov_b32_e32 v151, v199
	v_mov_b32_e32 v149, v199
	v_cndmask_b32_e32 v198, 0, v250, vcc
	v_lshl_add_u64 v[144:145], s[34:35], 0, v[198:199]
	v_lshl_add_u64 v[144:145], v[144:145], 0, v[162:163]
	v_lshl_add_u64 v[144:145], v[144:145], 0, v[150:151]
	v_lshl_add_u64 v[144:145], v[144:145], 0, v[148:149]
	global_store_dwordx4 v[144:145], v[60:63], off
	global_store_dwordx4 v[144:145], v[52:55], off offset:64
	global_store_dwordx4 v[144:145], v[56:59], off offset:128
	global_store_dwordx4 v[144:145], v[48:51], off offset:192

.LBB0_206:
	s_or_b64 exec, exec, s[52:53]
	v_cmp_gt_i32_e32 vcc, s22, v137
	s_ashr_i32 s89, s88, 31
	v_ashrrev_i32_e32 v159, 31, v158
	v_cndmask_b32_e32 v136, 1.0, v249, vcc
	v_lshl_add_u64 v[138:139], v[158:159], 0, s[88:89]
	v_lshl_add_u64 v[158:159], v[138:139], 1, v[164:165]
	v_pk_mul_f32 v[160:161], v[136:137], v[144:145] op_sel_hi:[0,1]
	v_pk_mul_f32 v[164:165], v[136:137], v[146:147] op_sel_hi:[0,1]
	v_cvt_pk_bf16_f32 v160, v160, v161
	v_cvt_pk_bf16_f32 v161, v164, v165
	ds_write_b64 v200, v[160:161]
	v_pk_mul_f32 v[160:161], v[136:137], v[140:141] op_sel_hi:[0,1]
	v_pk_mul_f32 v[164:165], v[136:137], v[142:143] op_sel_hi:[0,1]
	v_cvt_pk_bf16_f32 v160, v160, v161
	v_cvt_pk_bf16_f32 v161, v164, v165
	ds_write_b64 v200, v[160:161] offset:32
	v_pk_mul_f32 v[160:161], v[136:137], v[132:133] op_sel_hi:[0,1]
	v_pk_mul_f32 v[164:165], v[136:137], v[134:135] op_sel_hi:[0,1]
	v_cvt_pk_bf16_f32 v160, v160, v161
	v_cvt_pk_bf16_f32 v161, v164, v165
	ds_write_b64 v200, v[160:161] offset:64
	v_pk_mul_f32 v[160:161], v[136:137], v[128:129] op_sel_hi:[0,1]
	v_pk_mul_f32 v[164:165], v[136:137], v[130:131] op_sel_hi:[0,1]
	v_and_b32_e32 v149, 0xffffff00, v137
	v_cvt_pk_bf16_f32 v160, v160, v161
	v_cvt_pk_bf16_f32 v161, v164, v165
	v_cmp_eq_u32_e32 vcc, s22, v149
	ds_write_b64 v200, v[160:161] offset:96
	s_waitcnt lgkmcnt(0)
	ds_read_b128 v[204:207], v201
	ds_read_b128 v[208:211], v201 offset:1152
	v_lshl_add_u64 v[212:213], v[158:159], 0, v[202:203]
	v_lshl_add_u64 v[214:215], v[212:213], 0, s[100:101]
	s_waitcnt lgkmcnt(0)
	global_store_dwordx4 v[212:213], v[204:207], off offset:256
	global_store_dwordx4 v[214:215], v[208:211], off offset:256
	s_and_b64 s[88:89], s[54:55], vcc
	v_and_b32_e32 v158, 0x280, v137
	s_and_saveexec_b64 s[52:53], s[88:89]
	s_cbranch_execz .LBB0_208
	v_cmp_eq_u32_e32 vcc, s18, v158
	v_mov_b32_e32 v151, v199
	v_mov_b32_e32 v149, v199
	v_cndmask_b32_e32 v198, 0, v250, vcc
	v_lshl_add_u64 v[160:161], s[34:35], 0, v[198:199]
	v_lshl_add_u64 v[160:161], v[160:161], 0, v[162:163]
	v_lshl_add_u64 v[160:161], v[160:161], 0, v[150:151]
	v_lshl_add_u64 v[160:161], v[160:161], 0, v[148:149]
	global_store_dwordx4 v[160:161], v[144:147], off
	global_store_dwordx4 v[160:161], v[140:143], off offset:64
	global_store_dwordx4 v[160:161], v[132:135], off offset:128
	global_store_dwordx4 v[160:161], v[128:131], off offset:192

.LBB0_210:
	s_or_b64 exec, exec, s[52:53]
	v_mov_b32_e32 v155, v154
	v_mad_i64_i32 v[126:127], s[52:53], v137, s62, v[156:157]
	v_pk_mul_f32 v[142:143], v[154:155], v[128:129]
	v_pk_mul_f32 v[144:145], v[154:155], v[130:131]
	v_lshl_add_u64 v[140:141], v[152:153], 1, v[126:127]
	v_cvt_pk_bf16_f32 v142, v142, v143
	v_cvt_pk_bf16_f32 v143, v144, v145
	ds_write_b64 v200, v[142:143]
	v_pk_mul_f32 v[142:143], v[154:155], v[120:121]
	v_pk_mul_f32 v[144:145], v[154:155], v[122:123]
	v_cvt_pk_bf16_f32 v142, v142, v143
	v_cvt_pk_bf16_f32 v143, v144, v145
	ds_write_b64 v200, v[142:143] offset:32
	v_pk_mul_f32 v[142:143], v[154:155], v[116:117]
	v_pk_mul_f32 v[144:145], v[154:155], v[118:119]
	v_or_b32_e32 v124, s23, v133
	v_cvt_pk_bf16_f32 v142, v142, v143
	v_cvt_pk_bf16_f32 v143, v144, v145
	v_ashrrev_i32_e32 v125, 31, v124
	ds_write_b64 v200, v[142:143] offset:64
	v_pk_mul_f32 v[142:143], v[154:155], v[112:113]
	v_pk_mul_f32 v[144:145], v[154:155], v[114:115]
	v_lshlrev_b64 v[124:125], 9, v[124:125]
	v_cvt_pk_bf16_f32 v142, v142, v143
	v_cvt_pk_bf16_f32 v143, v144, v145
	ds_write_b64 v200, v[142:143] offset:96
	s_waitcnt lgkmcnt(0)
	ds_read_b128 v[204:207], v201
	ds_read_b128 v[208:211], v201 offset:1152
	v_lshl_add_u64 v[212:213], v[140:141], 0, v[202:203]
	v_lshl_add_u64 v[214:215], v[212:213], 0, s[100:101]
	s_waitcnt lgkmcnt(0)
	global_store_dwordx4 v[212:213], v[204:207], off
	global_store_dwordx4 v[214:215], v[208:211], off
	s_and_saveexec_b64 s[52:53], s[92:93]
	s_cbranch_execz .LBB0_212
	v_cmp_eq_u32_e32 vcc, s18, v168
	v_mov_b32_e32 v151, v199
	v_mov_b32_e32 v149, v199
	v_cndmask_b32_e32 v198, 0, v250, vcc
	v_lshl_add_u64 v[140:141], s[34:35], 0, v[198:199]
	v_lshl_add_u64 v[140:141], v[140:141], 0, v[124:125]
	v_lshl_add_u64 v[140:141], v[140:141], 0, v[150:151]
	v_lshl_add_u64 v[140:141], v[140:141], 0, v[148:149]
	global_store_dwordx4 v[140:141], v[128:131], off
	global_store_dwordx4 v[140:141], v[120:123], off offset:64
	global_store_dwordx4 v[140:141], v[116:119], off offset:128
	global_store_dwordx4 v[140:141], v[112:115], off offset:192

.LBB0_214:
	s_or_b64 exec, exec, s[52:53]
	v_mov_b32_e32 v137, v136
	v_pk_mul_f32 v[110:111], v[136:137], v[112:113]
	v_pk_mul_f32 v[116:117], v[136:137], v[114:115]
	v_lshl_add_u64 v[108:109], v[138:139], 1, v[126:127]
	v_cvt_pk_bf16_f32 v110, v110, v111
	v_cvt_pk_bf16_f32 v111, v116, v117
	ds_write_b64 v200, v[110:111]
	v_pk_mul_f32 v[110:111], v[136:137], v[104:105]
	v_pk_mul_f32 v[116:117], v[136:137], v[106:107]
	v_cvt_pk_bf16_f32 v110, v110, v111
	v_cvt_pk_bf16_f32 v111, v116, v117
	ds_write_b64 v200, v[110:111] offset:32
	v_pk_mul_f32 v[110:111], v[136:137], v[100:101]
	v_pk_mul_f32 v[116:117], v[136:137], v[102:103]
	v_cvt_pk_bf16_f32 v110, v110, v111
	v_cvt_pk_bf16_f32 v111, v116, v117
	ds_write_b64 v200, v[110:111] offset:64
	v_pk_mul_f32 v[110:111], v[136:137], v[96:97]
	v_pk_mul_f32 v[116:117], v[136:137], v[98:99]
	v_cvt_pk_bf16_f32 v110, v110, v111
	v_cvt_pk_bf16_f32 v111, v116, v117
	ds_write_b64 v200, v[110:111] offset:96
	s_waitcnt lgkmcnt(0)
	ds_read_b128 v[204:207], v201
	ds_read_b128 v[208:211], v201 offset:1152
	v_lshl_add_u64 v[212:213], v[108:109], 0, v[202:203]
	v_lshl_add_u64 v[214:215], v[212:213], 0, s[100:101]
	s_waitcnt lgkmcnt(0)
	global_store_dwordx4 v[212:213], v[204:207], off offset:256
	global_store_dwordx4 v[214:215], v[208:211], off offset:256
	s_and_saveexec_b64 s[52:53], s[88:89]
	s_cbranch_execz .LBB0_216
	v_cmp_eq_u32_e32 vcc, s18, v158
	v_mov_b32_e32 v151, v199
	v_mov_b32_e32 v149, v199
	v_cndmask_b32_e32 v198, 0, v250, vcc
	v_lshl_add_u64 v[108:109], s[34:35], 0, v[198:199]
	v_lshl_add_u64 v[108:109], v[108:109], 0, v[124:125]
	v_lshl_add_u64 v[108:109], v[108:109], 0, v[150:151]
	v_lshl_add_u64 v[108:109], v[108:109], 0, v[148:149]
	global_store_dwordx4 v[108:109], v[112:115], off
	global_store_dwordx4 v[108:109], v[104:107], off offset:64
	global_store_dwordx4 v[108:109], v[100:103], off offset:128
	global_store_dwordx4 v[108:109], v[96:99], off offset:192

.LBB0_218:
	s_or_b64 exec, exec, s[52:53]
	v_mad_i64_i32 v[94:95], s[52:53], v103, s62, v[156:157]
	v_pk_mul_f32 v[106:107], v[154:155], v[96:97]
	v_pk_mul_f32 v[108:109], v[154:155], v[98:99]
	v_lshl_add_u64 v[104:105], v[152:153], 1, v[94:95]
	v_cvt_pk_bf16_f32 v106, v106, v107
	v_cvt_pk_bf16_f32 v107, v108, v109
	ds_write_b64 v200, v[106:107]
	v_pk_mul_f32 v[106:107], v[154:155], v[88:89]
	v_pk_mul_f32 v[108:109], v[154:155], v[90:91]
	v_cvt_pk_bf16_f32 v106, v106, v107
	v_cvt_pk_bf16_f32 v107, v108, v109
	ds_write_b64 v200, v[106:107] offset:32
	v_pk_mul_f32 v[106:107], v[154:155], v[84:85]
	v_pk_mul_f32 v[108:109], v[154:155], v[86:87]
	v_or_b32_e32 v92, s23, v101
	v_cvt_pk_bf16_f32 v106, v106, v107
	v_cvt_pk_bf16_f32 v107, v108, v109
	v_ashrrev_i32_e32 v93, 31, v92
	ds_write_b64 v200, v[106:107] offset:64
	v_pk_mul_f32 v[106:107], v[154:155], v[80:81]
	v_pk_mul_f32 v[108:109], v[154:155], v[82:83]
	v_lshlrev_b64 v[92:93], 9, v[92:93]
	v_cvt_pk_bf16_f32 v106, v106, v107
	v_cvt_pk_bf16_f32 v107, v108, v109
	ds_write_b64 v200, v[106:107] offset:96
	s_waitcnt lgkmcnt(0)
	ds_read_b128 v[204:207], v201
	ds_read_b128 v[208:211], v201 offset:1152
	v_lshl_add_u64 v[212:213], v[104:105], 0, v[202:203]
	v_lshl_add_u64 v[214:215], v[212:213], 0, s[100:101]
	s_waitcnt lgkmcnt(0)
	global_store_dwordx4 v[212:213], v[204:207], off
	global_store_dwordx4 v[214:215], v[208:211], off
	s_and_saveexec_b64 s[52:53], s[92:93]
	s_cbranch_execz .LBB0_220
	v_cmp_eq_u32_e32 vcc, s18, v168
	v_mov_b32_e32 v151, v199
	v_mov_b32_e32 v149, v199
	v_cndmask_b32_e32 v198, 0, v250, vcc
	v_lshl_add_u64 v[104:105], s[34:35], 0, v[198:199]
	v_lshl_add_u64 v[104:105], v[104:105], 0, v[92:93]
	v_lshl_add_u64 v[104:105], v[104:105], 0, v[150:151]
	v_lshl_add_u64 v[104:105], v[104:105], 0, v[148:149]
	global_store_dwordx4 v[104:105], v[96:99], off
	global_store_dwordx4 v[104:105], v[88:91], off offset:64
	global_store_dwordx4 v[104:105], v[84:87], off offset:128
	global_store_dwordx4 v[104:105], v[80:83], off offset:192

.LBB0_222:
	s_or_b64 exec, exec, s[52:53]
	v_pk_mul_f32 v[78:79], v[136:137], v[80:81]
	v_pk_mul_f32 v[84:85], v[136:137], v[82:83]
	v_lshl_add_u64 v[76:77], v[138:139], 1, v[94:95]
	v_cvt_pk_bf16_f32 v78, v78, v79
	v_cvt_pk_bf16_f32 v79, v84, v85
	ds_write_b64 v200, v[78:79]
	v_pk_mul_f32 v[78:79], v[136:137], v[72:73]
	v_pk_mul_f32 v[84:85], v[136:137], v[74:75]
	v_cvt_pk_bf16_f32 v78, v78, v79
	v_cvt_pk_bf16_f32 v79, v84, v85
	ds_write_b64 v200, v[78:79] offset:32
	v_pk_mul_f32 v[78:79], v[136:137], v[68:69]
	v_pk_mul_f32 v[84:85], v[136:137], v[70:71]
	v_cvt_pk_bf16_f32 v78, v78, v79
	v_cvt_pk_bf16_f32 v79, v84, v85
	ds_write_b64 v200, v[78:79] offset:64
	v_pk_mul_f32 v[78:79], v[136:137], v[64:65]
	v_pk_mul_f32 v[84:85], v[136:137], v[66:67]
	v_cvt_pk_bf16_f32 v78, v78, v79
	v_cvt_pk_bf16_f32 v79, v84, v85
	ds_write_b64 v200, v[78:79] offset:96
	s_waitcnt lgkmcnt(0)
	ds_read_b128 v[204:207], v201
	ds_read_b128 v[208:211], v201 offset:1152
	v_lshl_add_u64 v[212:213], v[76:77], 0, v[202:203]
	v_lshl_add_u64 v[214:215], v[212:213], 0, s[100:101]
	s_waitcnt lgkmcnt(0)
	global_store_dwordx4 v[212:213], v[204:207], off offset:256
	global_store_dwordx4 v[214:215], v[208:211], off offset:256
	s_and_saveexec_b64 s[52:53], s[88:89]
	s_cbranch_execz .LBB0_224
	v_cmp_eq_u32_e32 vcc, s18, v158
	v_mov_b32_e32 v151, v199
	v_mov_b32_e32 v149, v199
	v_cndmask_b32_e32 v198, 0, v250, vcc
	v_lshl_add_u64 v[76:77], s[34:35], 0, v[198:199]
	v_lshl_add_u64 v[76:77], v[76:77], 0, v[92:93]
	v_lshl_add_u64 v[76:77], v[76:77], 0, v[150:151]
	v_lshl_add_u64 v[76:77], v[76:77], 0, v[148:149]
	global_store_dwordx4 v[76:77], v[80:83], off
	global_store_dwordx4 v[76:77], v[72:75], off offset:64
	global_store_dwordx4 v[76:77], v[68:71], off offset:128
	global_store_dwordx4 v[76:77], v[64:67], off offset:192

.LBB0_226:
	s_or_b64 exec, exec, s[12:13]
	v_mad_i64_i32 v[30:31], s[12:13], v66, s62, v[156:157]
	v_pk_mul_f32 v[40:41], v[154:155], v[32:33]
	v_pk_mul_f32 v[42:43], v[154:155], v[34:35]
	v_lshl_add_u64 v[38:39], v[152:153], 1, v[30:31]
	v_cvt_pk_bf16_f32 v40, v40, v41
	v_cvt_pk_bf16_f32 v41, v42, v43
	ds_write_b64 v200, v[40:41]
	v_pk_mul_f32 v[40:41], v[154:155], v[24:25]
	v_pk_mul_f32 v[42:43], v[154:155], v[26:27]
	v_cvt_pk_bf16_f32 v40, v40, v41
	v_cvt_pk_bf16_f32 v41, v42, v43
	ds_write_b64 v200, v[40:41] offset:32
	v_pk_mul_f32 v[40:41], v[154:155], v[20:21]
	v_pk_mul_f32 v[42:43], v[154:155], v[22:23]
	v_or_b32_e32 v28, s23, v65
	v_cvt_pk_bf16_f32 v40, v40, v41
	v_cvt_pk_bf16_f32 v41, v42, v43
	v_ashrrev_i32_e32 v29, 31, v28
	ds_write_b64 v200, v[40:41] offset:64
	v_pk_mul_f32 v[40:41], v[154:155], v[16:17]
	v_pk_mul_f32 v[42:43], v[154:155], v[18:19]
	v_lshlrev_b64 v[28:29], 9, v[28:29]
	v_cvt_pk_bf16_f32 v40, v40, v41
	v_cvt_pk_bf16_f32 v41, v42, v43
	ds_write_b64 v200, v[40:41] offset:96
	s_waitcnt lgkmcnt(0)
	ds_read_b128 v[204:207], v201
	ds_read_b128 v[208:211], v201 offset:1152
	v_lshl_add_u64 v[212:213], v[38:39], 0, v[202:203]
	v_lshl_add_u64 v[214:215], v[212:213], 0, s[100:101]
	s_waitcnt lgkmcnt(0)
	global_store_dwordx4 v[212:213], v[204:207], off
	global_store_dwordx4 v[214:215], v[208:211], off
	s_and_saveexec_b64 s[12:13], s[92:93]
	s_cbranch_execz .LBB0_228
	v_cmp_eq_u32_e32 vcc, s18, v168
	v_mov_b32_e32 v151, v199
	v_mov_b32_e32 v149, v199
	v_cndmask_b32_e32 v198, 0, v250, vcc
	v_lshl_add_u64 v[38:39], s[34:35], 0, v[198:199]
	v_lshl_add_u64 v[38:39], v[38:39], 0, v[28:29]
	v_lshl_add_u64 v[38:39], v[38:39], 0, v[150:151]
	v_lshl_add_u64 v[38:39], v[38:39], 0, v[148:149]
	global_store_dwordx4 v[38:39], v[32:35], off
	global_store_dwordx4 v[38:39], v[24:27], off offset:64
	global_store_dwordx4 v[38:39], v[20:23], off offset:128
	global_store_dwordx4 v[38:39], v[16:19], off offset:192

.LBB0_230:
	s_or_b64 exec, exec, s[12:13]
	v_pk_mul_f32 v[14:15], v[136:137], v[16:17]
	v_pk_mul_f32 v[20:21], v[136:137], v[18:19]
	v_lshl_add_u64 v[12:13], v[138:139], 1, v[30:31]
	v_cvt_pk_bf16_f32 v14, v14, v15
	v_cvt_pk_bf16_f32 v15, v20, v21
	ds_write_b64 v200, v[14:15]
	v_pk_mul_f32 v[14:15], v[136:137], v[8:9]
	v_pk_mul_f32 v[20:21], v[136:137], v[10:11]
	v_cvt_pk_bf16_f32 v14, v14, v15
	v_cvt_pk_bf16_f32 v15, v20, v21
	ds_write_b64 v200, v[14:15] offset:32
	v_pk_mul_f32 v[14:15], v[136:137], v[4:5]
	v_pk_mul_f32 v[20:21], v[136:137], v[6:7]
	v_cvt_pk_bf16_f32 v14, v14, v15
	v_cvt_pk_bf16_f32 v15, v20, v21
	ds_write_b64 v200, v[14:15] offset:64
	v_pk_mul_f32 v[14:15], v[136:137], v[0:1]
	v_pk_mul_f32 v[20:21], v[136:137], v[2:3]
	v_cvt_pk_bf16_f32 v14, v14, v15
	v_cvt_pk_bf16_f32 v15, v20, v21
	ds_write_b64 v200, v[14:15] offset:96
	s_waitcnt lgkmcnt(0)
	ds_read_b128 v[204:207], v201
	ds_read_b128 v[208:211], v201 offset:1152
	v_lshl_add_u64 v[212:213], v[12:13], 0, v[202:203]
	v_lshl_add_u64 v[214:215], v[212:213], 0, s[100:101]
	s_waitcnt lgkmcnt(0)
	global_store_dwordx4 v[212:213], v[204:207], off offset:256
	global_store_dwordx4 v[214:215], v[208:211], off offset:256
	s_and_saveexec_b64 s[12:13], s[88:89]
	s_cbranch_execz .LBB0_189
	v_cmp_eq_u32_e32 vcc, s18, v158
	v_mov_b32_e32 v151, v199
	v_mov_b32_e32 v149, v199
	v_cndmask_b32_e32 v198, 0, v250, vcc
	v_lshl_add_u64 v[12:13], s[34:35], 0, v[198:199]
	v_lshl_add_u64 v[12:13], v[12:13], 0, v[28:29]
	v_lshl_add_u64 v[12:13], v[12:13], 0, v[150:151]
	v_lshl_add_u64 v[12:13], v[12:13], 0, v[148:149]
	global_store_dwordx4 v[12:13], v[16:19], off
	global_store_dwordx4 v[12:13], v[8:11], off offset:64
	global_store_dwordx4 v[12:13], v[4:7], off offset:128
	global_store_dwordx4 v[12:13], v[0:3], off offset:192
	s_branch .LBB0_189
